# P1 schedule: conv-tile units dealt first (3 per workgroup), plain units after, XCD-major slot order
# speedup vs baseline: 1.0010x; 1.0010x over previous
;     __host__ __device__ bool next(int i, Unit& u) const {
;         const long L = (long)i * G + c; if (L >= nwg) return false;
;         int wgid = (int)L; { const int q = nwg / NXCD, r = nwg % NXCD, xcd = wgid % NXCD, off = wgid / NXCD; wgid = (xcd < r ? xcd * (q + 1) : r * (q + 1) + (xcd - r) * q) + off; }
;         const int nig = WGM * nN, gid = wgid / nig, fm = gid * WGM, gsz = (nM - fm) < WGM ? (nM - fm) : WGM;
;         u.pm = fm + ((wgid % nig) % gsz); u.pn = (wgid % nig) / gsz; return true;
; template <class Epi, class Sched, bool ALIGN_EPI = true>
; __device__ __forceinline__ void gemm_phase(LAS unsigned char* lds, const Gemm g, const Sched& S, const Epi& E) {
;     ...
;     if (!S.next(0, cur)) return;
.LBB0_113:
	s_or_b64 exec, exec, s[0:1]
	v_mov_b32_e32 v4, v181
	s_cmpk_lt_i32 s88, 0xbc5
	s_waitcnt lgkmcnt(0)
	s_barrier
	s_cselect_b64 s[0:1], -1, 0
	s_cmpk_gt_i32 s88, 0xbc4
	v_readfirstlane_b32 s4, v4
	s_cbranch_scc1 .LBB0_119
	s_and_b32 s3, s88, 7
	s_lshl_b32 s3, s3, 5
	s_lshr_b32 s5, s88, 3
	s_add_i32 s3, s3, s5
	s_mul_hi_u32 s22, s3, 0xaaaaaaab
	s_lshr_b32 s22, s22, 2
	s_mul_i32 s5, s22, 6
	s_sub_i32 s2, s3, s5
	s_add_i32 s2, s2, 4

;     __host__ __device__ bool next(int i, Unit& u) const {
;         const long L = (long)i * G + c; if (L >= nwg) return false;
;         int wgid = (int)L; { const int q = nwg / NXCD, r = nwg % NXCD, xcd = wgid % NXCD, off = wgid / NXCD; wgid = (xcd < r ? xcd * (q + 1) : r * (q + 1) + (xcd - r) * q) + off; }
;         const int nig = WGM * nN, gid = wgid / nig, fm = gid * WGM, gsz = (nM - fm) < WGM ? (nM - fm) : WGM;
;         u.pm = fm + ((wgid % nig) % gsz); u.pn = (wgid % nig) / gsz; return true;
; template <class Epi, class Sched, bool ALIGN_EPI = true>
; __device__ __forceinline__ void gemm_phase(LAS unsigned char* lds, const Gemm g, const Sched& S, const Epi& E) {
;     ...
;         const bool has_next = S.next(ui + 1, nxt);
.LBB0_125:
	s_add_i32 s29, s29, 1
	s_mul_i32 s0, s29, s45
	s_mul_hi_u32 s1, s29, s46
	s_add_i32 s1, s1, s0
	s_mul_i32 s0, s29, s46
	s_add_u32 s0, s0, s88
	s_addc_u32 s1, s1, s47
	v_cmp_gt_i64_e32 vcc, s[0:1], v[144:145]
	v_cmp_lt_i64_e64 s[4:5], s[0:1], v[142:143]
	s_cbranch_vccnz .LBB0_131
	s_and_b32 s0, s88, 7
	s_lshl_b32 s0, s0, 5
	s_lshr_b32 s1, s88, 3
	s_add_i32 s0, s0, s1
	s_cmp_lt_u32 s29, 3
	s_cbranch_scc1 .Lp1s_conv
	s_cmp_eq_u32 s29, 3
	s_cbranch_scc0 .Lp1s_plain_gt3
	s_cmp_lt_u32 s0, 18
	s_cbranch_scc0 .Lp1s_plain3
	s_addk_i32 s0, 0x300
	s_branch .Lp1s_convq
.Lp1s_plain3:
	s_add_i32 s0, s0, -18
	s_branch .Lp1s_plainP
.Lp1s_plain_gt3:
	s_cmp_eq_u32 s29, 11
	s_cbranch_scc1 .Lp1s_plain11
	s_lshl_b32 s1, s29, 8
	s_add_i32 s0, s0, s1
	s_add_i32 s0, s0, 0xfffffcee
	s_branch .Lp1s_plainP
.Lp1s_plain11:
	s_add_i32 s0, s88, 0x7ee
.Lp1s_plainP:
	s_mul_hi_u32 s57, s0, 0xf0f0f0f1
	s_lshr_b32 s57, s57, 4
	s_mul_i32 s1, s57, 17
	s_sub_i32 s16, s0, s1
	s_cmp_lt_u32 s16, 4
	s_cbranch_scc1 .Lp1s_done
	s_add_i32 s16, s16, 6
	s_branch .Lp1s_done
.Lp1s_conv:
	s_lshl_b32 s1, s29, 8
	s_add_i32 s0, s0, s1
.Lp1s_convq:
	s_mul_hi_u32 s57, s0, 0xaaaaaaab
	s_lshr_b32 s57, s57, 2
	s_mul_i32 s1, s57, 6
	s_sub_i32 s16, s0, s1
	s_add_i32 s16, s16, 4
.Lp1s_done:
.LBB0_131:
	s_nop 0
	v_cndmask_b32_e64 v0, 0, 1, s[4:5]
	v_cmp_ne_u32_e64 s[0:1], 1, v0
	s_andn2_b64 vcc, exec, s[4:5]
	s_mov_b64 s[18:19], s[8:9]
	s_cbranch_vccnz .LBB0_133
	s_mul_i32 s17, s57, 0x7e800
	v_readlane_b32 s18, v237, 54
	s_mul_hi_i32 s3, s57, 0x7e800
	v_readlane_b32 s19, v237, 55
	s_add_u32 s17, s18, s17
	s_addc_u32 s3, s19, s3
	s_add_u32 s18, s17, 0xffffe800
	s_addc_u32 s19, s3, -1
